# small-gemm K-section coalesced also in P5 (K=2816, lines dealt 6/5 per wave)
# speedup vs baseline: 1.0347x; 1.0157x over previous
; #define HG_MFMA(a, b, c) __builtin_amdgcn_mfma_f32_32x32x16_bf16((a), (b), (c), 0, 0, 0)
;     __device__ __forceinline__ void small_pre(int row, int c0, int c1, SPre& sp) const { sp.ss = sumsq2[row]; sp.h0 = unpack4(*(const u32x2*)(HB + (size_t)row * DM + c0)); sp.h1 = unpack4(*(const u32x2*)(HB + (size_t)row * DM + c1)); }
; template <int K, class Epi>
; __device__ __forceinline__ void small_gemm(unsigned char* lds, const bf16_t* A, const bf16_t* Bt, int row0, int br0, int br1, const Epi& E) {
;     int tid = threadIdx.x; asm volatile("" : "+v"(tid));
;     const int w = __builtin_amdgcn_readfirstlane(tid >> 6), lane = tid & 63, r = lane & 31, hh = lane >> 5;
;     constexpr int ks = K >> 3, NS = ks >> 4, UNR = NS <= 8 ? NS : 11; const int k0 = w * ks + 8 * hh;
;     const bf16_t* ap = A + (size_t)(row0 + r) * K + k0; const bf16_t* b0p = Bt + (size_t)(br0 + r) * K + k0; const bf16_t* b1p = Bt + (size_t)(br1 + r) * K + k0;
;     typename Epi::SPre spre; const int srow = row0 + ((tid >> 3) & 31), sc4 = (tid & 7) * 4;
;     if (tid < 256) E.small_pre(srow, br0 + sc4, br1 + sc4, spre);
;     f32x16 acc0, acc1;
; #pragma unroll
;     for (int i = 0; i < 16; ++i) { acc0[i] = 0.f; acc1[i] = 0.f; }
; #pragma unroll UNR
;     for (int s = 0; s < NS; ++s) { const bf16x8 a = *(const bf16x8*)(ap + 16 * s), b0 = *(const bf16x8*)(b0p + 16 * s), b1 = *(const bf16x8*)(b1p + 16 * s);
;         acc0 = HG_MFMA(a, b0, acc0); acc1 = HG_MFMA(a, b1, acc1); }
.LBB0_791:
	s_or_b64 exec, exec, s[8:9]
	v_and_b32_e32 v35, 31, v52
	s_ashr_i32 s18, s11, 6
	v_bfe_u32 v37, v52, 5, 1
	s_waitcnt lgkmcnt(0)
	s_mul_i32 s52, s18, 6
	s_mul_i32 s53, s18, 5
	s_add_i32 s53, s53, 4
	s_cmp_lt_u32 s18, 4
	s_cselect_b32 s52, s52, s53
	s_lshl_b32 s53, s52, 7
	s_and_b32 s52, s0, 0xffffffe0
	s_addk_i32 s52, 0x4000
	s_mul_i32 s52, s52, 0x1600
	s_add_i32 s52, s52, s53
	s_add_u32 s54, s64, s52
	s_addc_u32 s55, s65, 0
	s_add_u32 s54, s54, 0x96f5e00
	s_addc_u32 s55, s55, 0
	s_mul_i32 s52, s10, 0x1600
	s_add_i32 s52, s52, s53
	s_add_u32 s56, s64, s52
	s_addc_u32 s57, s65, 0
	s_add_u32 s56, s56, 0x1300000
	s_addc_u32 s57, s57, 0
	s_add_u32 s58, s56, 0x2c000
	s_addc_u32 s59, s57, 0
	v_and_b32_e32 v60, 63, v52
	v_lshrrev_b32_e32 v61, 4, v60
	v_and_b32_e32 v62, 7, v60
	v_xor_b32_e32 v62, v62, v61
	v_lshrrev_b32_e32 v61, 3, v60
	v_lshlrev_b32_e32 v62, 4, v62
	v_mul_u32_u24_e32 v61, 0x1600, v61
	v_or_b32_e32 v64, v61, v62
	v_xor_b32_e32 v65, 64, v64
	v_add_u32_e32 v65, 0xb000, v65
	v_add_u32_e32 v66, 0x16000, v64
	v_xor_b32_e32 v67, 64, v64
	v_add_u32_e32 v67, 0x21000, v67
	global_load_dwordx4 v[88:91], v64, s[54:55]
	global_load_dwordx4 v[92:95], v65, s[54:55]
	global_load_dwordx4 v[96:99], v66, s[54:55]
	global_load_dwordx4 v[100:103], v67, s[54:55]
	global_load_dwordx4 v[104:107], v64, s[56:57]
	global_load_dwordx4 v[108:111], v65, s[56:57]
	global_load_dwordx4 v[112:115], v66, s[56:57]
	global_load_dwordx4 v[116:119], v67, s[56:57]
	global_load_dwordx4 v[120:123], v64, s[58:59]
	global_load_dwordx4 v[124:127], v65, s[58:59]
	global_load_dwordx4 v[128:131], v66, s[58:59]
	global_load_dwordx4 v[132:135], v67, s[58:59]
	global_load_dwordx4 v[136:139], v64, s[54:55] offset:128
	global_load_dwordx4 v[140:143], v65, s[54:55] offset:128
	global_load_dwordx4 v[144:147], v66, s[54:55] offset:128
	global_load_dwordx4 v[148:151], v67, s[54:55] offset:128
	global_load_dwordx4 v[152:155], v64, s[56:57] offset:128
	global_load_dwordx4 v[156:159], v65, s[56:57] offset:128
	global_load_dwordx4 v[160:163], v66, s[56:57] offset:128
	global_load_dwordx4 v[164:167], v67, s[56:57] offset:128
	global_load_dwordx4 v[168:171], v64, s[58:59] offset:128
	global_load_dwordx4 v[172:175], v65, s[58:59] offset:128
	global_load_dwordx4 v[180:183], v66, s[58:59] offset:128
	global_load_dwordx4 v[184:187], v67, s[58:59] offset:128
	s_mul_i32 s60, s18, 0x3000
	v_lshl_add_u32 v68, v60, 4, s60
	v_lshl_add_u32 v69, v35, 7, s60
	v_bfe_u32 v63, v35, 1, 3
	v_or_b32_e32 v46, 0, v37
	v_xor_b32_e32 v46, v46, v63
	v_lshl_add_u32 v46, v46, 4, v69
	v_or_b32_e32 v47, 2, v37
	v_xor_b32_e32 v47, v47, v63
	v_lshl_add_u32 v47, v47, 4, v69
	v_or_b32_e32 v48, 4, v37
	v_xor_b32_e32 v48, v48, v63
	v_lshl_add_u32 v48, v48, 4, v69
	v_or_b32_e32 v49, 6, v37
	v_xor_b32_e32 v49, v49, v63
	v_lshl_add_u32 v49, v49, 4, v69
	s_waitcnt vmcnt(12)
	ds_write_b128 v68, v[88:91]
	ds_write_b128 v68, v[92:95] offset:1024
	ds_write_b128 v68, v[96:99] offset:2048
	ds_write_b128 v68, v[100:103] offset:3072
	ds_write_b128 v68, v[104:107] offset:4096
	ds_write_b128 v68, v[108:111] offset:5120
	ds_write_b128 v68, v[112:115] offset:6144
	ds_write_b128 v68, v[116:119] offset:7168
	ds_write_b128 v68, v[120:123] offset:8192
	ds_write_b128 v68, v[124:127] offset:9216
	ds_write_b128 v68, v[128:131] offset:10240
	ds_write_b128 v68, v[132:135] offset:11264
	s_waitcnt lgkmcnt(0)
	global_load_dwordx4 v[88:91], v64, s[54:55] offset:256
	global_load_dwordx4 v[92:95], v65, s[54:55] offset:256
	global_load_dwordx4 v[96:99], v66, s[54:55] offset:256
	global_load_dwordx4 v[100:103], v67, s[54:55] offset:256
	global_load_dwordx4 v[104:107], v64, s[56:57] offset:256
	global_load_dwordx4 v[108:111], v65, s[56:57] offset:256
	global_load_dwordx4 v[112:115], v66, s[56:57] offset:256
	global_load_dwordx4 v[116:119], v67, s[56:57] offset:256
	global_load_dwordx4 v[120:123], v64, s[58:59] offset:256
	global_load_dwordx4 v[124:127], v65, s[58:59] offset:256
	global_load_dwordx4 v[128:131], v66, s[58:59] offset:256
	global_load_dwordx4 v[132:135], v67, s[58:59] offset:256
	ds_read_b128 v[192:195], v46
	ds_read_b128 v[212:215], v46 offset:4096
	ds_read_b128 v[228:231], v46 offset:8192
	ds_read_b128 v[196:199], v47
	ds_read_b128 v[216:219], v47 offset:4096
	ds_read_b128 v[232:235], v47 offset:8192
	ds_read_b128 v[200:203], v48
	ds_read_b128 v[220:223], v48 offset:4096
	ds_read_b128 v[236:239], v48 offset:8192
	ds_read_b128 v[208:211], v49
	ds_read_b128 v[224:227], v49 offset:4096
	ds_read_b128 v[240:243], v49 offset:8192
	s_waitcnt lgkmcnt(9)
	v_mfma_f32_32x32x16_bf16 v[0:15], v[192:195], v[212:215], 0
	v_mfma_f32_32x32x16_bf16 v[16:31], v[192:195], v[228:231], 0
	s_waitcnt lgkmcnt(6)
	v_mfma_f32_32x32x16_bf16 v[0:15], v[196:199], v[216:219], v[0:15]
	v_mfma_f32_32x32x16_bf16 v[16:31], v[196:199], v[232:235], v[16:31]
	s_waitcnt lgkmcnt(3)
	v_mfma_f32_32x32x16_bf16 v[0:15], v[200:203], v[220:223], v[0:15]
	v_mfma_f32_32x32x16_bf16 v[16:31], v[200:203], v[236:239], v[16:31]
	s_waitcnt lgkmcnt(0)
	v_mfma_f32_32x32x16_bf16 v[0:15], v[208:211], v[224:227], v[0:15]
	v_mfma_f32_32x32x16_bf16 v[16:31], v[208:211], v[240:243], v[16:31]
	s_waitcnt vmcnt(12)
	ds_write_b128 v68, v[136:139]
	ds_write_b128 v68, v[140:143] offset:1024
	ds_write_b128 v68, v[144:147] offset:2048
	ds_write_b128 v68, v[148:151] offset:3072
	ds_write_b128 v68, v[152:155] offset:4096
	ds_write_b128 v68, v[156:159] offset:5120
	ds_write_b128 v68, v[160:163] offset:6144
	ds_write_b128 v68, v[164:167] offset:7168
	ds_write_b128 v68, v[168:171] offset:8192
	ds_write_b128 v68, v[172:175] offset:9216
	ds_write_b128 v68, v[180:183] offset:10240
	ds_write_b128 v68, v[184:187] offset:11264
	s_waitcnt lgkmcnt(0)
; #define HG_MFMA(a, b, c) __builtin_amdgcn_mfma_f32_32x32x16_bf16((a), (b), (c), 0, 0, 0)
; template <int K, class Epi>
; __device__ __forceinline__ void small_gemm(unsigned char* lds, const bf16_t* A, const bf16_t* Bt, int row0, int br0, int br1, const Epi& E) {
;     ...
; #pragma unroll UNR
;     for (int s = 0; s < NS; ++s) { const bf16x8 a = *(const bf16x8*)(ap + 16 * s), b0 = *(const bf16x8*)(b0p + 16 * s), b1 = *(const bf16x8*)(b1p + 16 * s);
;         acc0 = HG_MFMA(a, b0, acc0); acc1 = HG_MFMA(a, b1, acc1); }
	global_load_dwordx4 v[136:139], v64, s[54:55] offset:384
	global_load_dwordx4 v[140:143], v65, s[54:55] offset:384
	global_load_dwordx4 v[144:147], v66, s[54:55] offset:384
	global_load_dwordx4 v[148:151], v67, s[54:55] offset:384
	global_load_dwordx4 v[152:155], v64, s[56:57] offset:384
	global_load_dwordx4 v[156:159], v65, s[56:57] offset:384
	global_load_dwordx4 v[160:163], v66, s[56:57] offset:384
	global_load_dwordx4 v[164:167], v67, s[56:57] offset:384
	global_load_dwordx4 v[168:171], v64, s[58:59] offset:384
	global_load_dwordx4 v[172:175], v65, s[58:59] offset:384
	global_load_dwordx4 v[180:183], v66, s[58:59] offset:384
	global_load_dwordx4 v[184:187], v67, s[58:59] offset:384
	ds_read_b128 v[192:195], v46
	ds_read_b128 v[212:215], v46 offset:4096
	ds_read_b128 v[228:231], v46 offset:8192
	ds_read_b128 v[196:199], v47
	ds_read_b128 v[216:219], v47 offset:4096
	ds_read_b128 v[232:235], v47 offset:8192
	ds_read_b128 v[200:203], v48
	ds_read_b128 v[220:223], v48 offset:4096
	ds_read_b128 v[236:239], v48 offset:8192
	ds_read_b128 v[208:211], v49
	ds_read_b128 v[224:227], v49 offset:4096
	ds_read_b128 v[240:243], v49 offset:8192
	s_waitcnt lgkmcnt(9)
	v_mfma_f32_32x32x16_bf16 v[0:15], v[192:195], v[212:215], v[0:15]
	v_mfma_f32_32x32x16_bf16 v[16:31], v[192:195], v[228:231], v[16:31]
	s_waitcnt lgkmcnt(6)
	v_mfma_f32_32x32x16_bf16 v[0:15], v[196:199], v[216:219], v[0:15]
	v_mfma_f32_32x32x16_bf16 v[16:31], v[196:199], v[232:235], v[16:31]
	s_waitcnt lgkmcnt(3)
	v_mfma_f32_32x32x16_bf16 v[0:15], v[200:203], v[220:223], v[0:15]
	v_mfma_f32_32x32x16_bf16 v[16:31], v[200:203], v[236:239], v[16:31]
	s_waitcnt lgkmcnt(0)
	v_mfma_f32_32x32x16_bf16 v[0:15], v[208:211], v[224:227], v[0:15]
	v_mfma_f32_32x32x16_bf16 v[16:31], v[208:211], v[240:243], v[16:31]
	s_waitcnt vmcnt(12)
	ds_write_b128 v68, v[88:91]
	ds_write_b128 v68, v[92:95] offset:1024
	ds_write_b128 v68, v[96:99] offset:2048
	ds_write_b128 v68, v[100:103] offset:3072
	ds_write_b128 v68, v[104:107] offset:4096
	ds_write_b128 v68, v[108:111] offset:5120
	ds_write_b128 v68, v[112:115] offset:6144
	ds_write_b128 v68, v[116:119] offset:7168
	ds_write_b128 v68, v[120:123] offset:8192
	ds_write_b128 v68, v[124:127] offset:9216
	ds_write_b128 v68, v[128:131] offset:10240
	ds_write_b128 v68, v[132:135] offset:11264
	s_waitcnt lgkmcnt(0)
	global_load_dwordx4 v[88:91], v64, s[54:55] offset:512
	global_load_dwordx4 v[92:95], v65, s[54:55] offset:512
	global_load_dwordx4 v[96:99], v66, s[54:55] offset:512
	global_load_dwordx4 v[100:103], v67, s[54:55] offset:512
	global_load_dwordx4 v[104:107], v64, s[56:57] offset:512
	global_load_dwordx4 v[108:111], v65, s[56:57] offset:512
	global_load_dwordx4 v[112:115], v66, s[56:57] offset:512
	global_load_dwordx4 v[116:119], v67, s[56:57] offset:512
	global_load_dwordx4 v[120:123], v64, s[58:59] offset:512
	global_load_dwordx4 v[124:127], v65, s[58:59] offset:512
	global_load_dwordx4 v[128:131], v66, s[58:59] offset:512
	global_load_dwordx4 v[132:135], v67, s[58:59] offset:512
	ds_read_b128 v[192:195], v46
	ds_read_b128 v[212:215], v46 offset:4096
	ds_read_b128 v[228:231], v46 offset:8192
	ds_read_b128 v[196:199], v47
	ds_read_b128 v[216:219], v47 offset:4096
	ds_read_b128 v[232:235], v47 offset:8192
	ds_read_b128 v[200:203], v48
	ds_read_b128 v[220:223], v48 offset:4096
	ds_read_b128 v[236:239], v48 offset:8192
	ds_read_b128 v[208:211], v49
	ds_read_b128 v[224:227], v49 offset:4096
	ds_read_b128 v[240:243], v49 offset:8192
	s_waitcnt lgkmcnt(9)
	v_mfma_f32_32x32x16_bf16 v[0:15], v[192:195], v[212:215], v[0:15]
	v_mfma_f32_32x32x16_bf16 v[16:31], v[192:195], v[228:231], v[16:31]
	s_waitcnt lgkmcnt(6)
	v_mfma_f32_32x32x16_bf16 v[0:15], v[196:199], v[216:219], v[0:15]
	v_mfma_f32_32x32x16_bf16 v[16:31], v[196:199], v[232:235], v[16:31]
	s_waitcnt lgkmcnt(3)
	v_mfma_f32_32x32x16_bf16 v[0:15], v[200:203], v[220:223], v[0:15]
	v_mfma_f32_32x32x16_bf16 v[16:31], v[200:203], v[236:239], v[16:31]
	s_waitcnt lgkmcnt(0)
	v_mfma_f32_32x32x16_bf16 v[0:15], v[208:211], v[224:227], v[0:15]
	v_mfma_f32_32x32x16_bf16 v[16:31], v[208:211], v[240:243], v[16:31]
	s_cmp_gt_u32 s18, 3
	s_cbranch_scc1 .Lsg5_short
	s_waitcnt vmcnt(12)
	ds_write_b128 v68, v[136:139]
	ds_write_b128 v68, v[140:143] offset:1024
	ds_write_b128 v68, v[144:147] offset:2048
	ds_write_b128 v68, v[148:151] offset:3072
	ds_write_b128 v68, v[152:155] offset:4096
	ds_write_b128 v68, v[156:159] offset:5120
	ds_write_b128 v68, v[160:163] offset:6144
	ds_write_b128 v68, v[164:167] offset:7168
	ds_write_b128 v68, v[168:171] offset:8192
	ds_write_b128 v68, v[172:175] offset:9216
	ds_write_b128 v68, v[180:183] offset:10240
	ds_write_b128 v68, v[184:187] offset:11264
	s_waitcnt lgkmcnt(0)
	global_load_dwordx4 v[136:139], v64, s[54:55] offset:640
	global_load_dwordx4 v[140:143], v65, s[54:55] offset:640
	global_load_dwordx4 v[144:147], v66, s[54:55] offset:640
	global_load_dwordx4 v[148:151], v67, s[54:55] offset:640
	global_load_dwordx4 v[152:155], v64, s[56:57] offset:640
	global_load_dwordx4 v[156:159], v65, s[56:57] offset:640
	global_load_dwordx4 v[160:163], v66, s[56:57] offset:640
	global_load_dwordx4 v[164:167], v67, s[56:57] offset:640
	global_load_dwordx4 v[168:171], v64, s[58:59] offset:640
	global_load_dwordx4 v[172:175], v65, s[58:59] offset:640
	global_load_dwordx4 v[180:183], v66, s[58:59] offset:640
	global_load_dwordx4 v[184:187], v67, s[58:59] offset:640
	ds_read_b128 v[192:195], v46
	ds_read_b128 v[212:215], v46 offset:4096
	ds_read_b128 v[228:231], v46 offset:8192
	ds_read_b128 v[196:199], v47
	ds_read_b128 v[216:219], v47 offset:4096
	ds_read_b128 v[232:235], v47 offset:8192
	ds_read_b128 v[200:203], v48
	ds_read_b128 v[220:223], v48 offset:4096
	ds_read_b128 v[236:239], v48 offset:8192
	ds_read_b128 v[208:211], v49
	ds_read_b128 v[224:227], v49 offset:4096
	ds_read_b128 v[240:243], v49 offset:8192
	s_waitcnt lgkmcnt(9)
; #define HG_MFMA(a, b, c) __builtin_amdgcn_mfma_f32_32x32x16_bf16((a), (b), (c), 0, 0, 0)
; template <int K, class Epi>
; __device__ __forceinline__ void small_gemm(unsigned char* lds, const bf16_t* A, const bf16_t* Bt, int row0, int br0, int br1, const Epi& E) {
;     ...
; #pragma unroll UNR
;     for (int s = 0; s < NS; ++s) { const bf16x8 a = *(const bf16x8*)(ap + 16 * s), b0 = *(const bf16x8*)(b0p + 16 * s), b1 = *(const bf16x8*)(b1p + 16 * s);
;         acc0 = HG_MFMA(a, b0, acc0); acc1 = HG_MFMA(a, b1, acc1); }
	v_mfma_f32_32x32x16_bf16 v[0:15], v[192:195], v[212:215], v[0:15]
	v_mfma_f32_32x32x16_bf16 v[16:31], v[192:195], v[228:231], v[16:31]
	s_waitcnt lgkmcnt(6)
	v_mfma_f32_32x32x16_bf16 v[0:15], v[196:199], v[216:219], v[0:15]
	v_mfma_f32_32x32x16_bf16 v[16:31], v[196:199], v[232:235], v[16:31]
	s_waitcnt lgkmcnt(3)
	v_mfma_f32_32x32x16_bf16 v[0:15], v[200:203], v[220:223], v[0:15]
	v_mfma_f32_32x32x16_bf16 v[16:31], v[200:203], v[236:239], v[16:31]
	s_waitcnt lgkmcnt(0)
	v_mfma_f32_32x32x16_bf16 v[0:15], v[208:211], v[224:227], v[0:15]
	v_mfma_f32_32x32x16_bf16 v[16:31], v[208:211], v[240:243], v[16:31]
	s_waitcnt vmcnt(12)
	ds_write_b128 v68, v[88:91]
	ds_write_b128 v68, v[92:95] offset:1024
	ds_write_b128 v68, v[96:99] offset:2048
	ds_write_b128 v68, v[100:103] offset:3072
	ds_write_b128 v68, v[104:107] offset:4096
	ds_write_b128 v68, v[108:111] offset:5120
	ds_write_b128 v68, v[112:115] offset:6144
	ds_write_b128 v68, v[116:119] offset:7168
	ds_write_b128 v68, v[120:123] offset:8192
	ds_write_b128 v68, v[124:127] offset:9216
	ds_write_b128 v68, v[128:131] offset:10240
	ds_write_b128 v68, v[132:135] offset:11264
	s_waitcnt lgkmcnt(0)
	ds_read_b128 v[192:195], v46
	ds_read_b128 v[212:215], v46 offset:4096
	ds_read_b128 v[228:231], v46 offset:8192
	ds_read_b128 v[196:199], v47
	ds_read_b128 v[216:219], v47 offset:4096
	ds_read_b128 v[232:235], v47 offset:8192
	ds_read_b128 v[200:203], v48
	ds_read_b128 v[220:223], v48 offset:4096
	ds_read_b128 v[236:239], v48 offset:8192
	ds_read_b128 v[208:211], v49
	ds_read_b128 v[224:227], v49 offset:4096
	ds_read_b128 v[240:243], v49 offset:8192
	s_waitcnt lgkmcnt(9)
	v_mfma_f32_32x32x16_bf16 v[0:15], v[192:195], v[212:215], v[0:15]
	v_mfma_f32_32x32x16_bf16 v[16:31], v[192:195], v[228:231], v[16:31]
	s_waitcnt lgkmcnt(6)
	v_mfma_f32_32x32x16_bf16 v[0:15], v[196:199], v[216:219], v[0:15]
	v_mfma_f32_32x32x16_bf16 v[16:31], v[196:199], v[232:235], v[16:31]
	s_waitcnt lgkmcnt(3)
	v_mfma_f32_32x32x16_bf16 v[0:15], v[200:203], v[220:223], v[0:15]
	v_mfma_f32_32x32x16_bf16 v[16:31], v[200:203], v[236:239], v[16:31]
	s_waitcnt lgkmcnt(0)
	v_mfma_f32_32x32x16_bf16 v[0:15], v[208:211], v[224:227], v[0:15]
	v_mfma_f32_32x32x16_bf16 v[16:31], v[208:211], v[240:243], v[16:31]
	s_waitcnt vmcnt(0)
	ds_write_b128 v68, v[136:139]
	ds_write_b128 v68, v[140:143] offset:1024
	ds_write_b128 v68, v[144:147] offset:2048
	ds_write_b128 v68, v[148:151] offset:3072
	ds_write_b128 v68, v[152:155] offset:4096
	ds_write_b128 v68, v[156:159] offset:5120
	ds_write_b128 v68, v[160:163] offset:6144
	ds_write_b128 v68, v[164:167] offset:7168
	ds_write_b128 v68, v[168:171] offset:8192
	ds_write_b128 v68, v[172:175] offset:9216
	ds_write_b128 v68, v[180:183] offset:10240
	ds_write_b128 v68, v[184:187] offset:11264
	s_waitcnt lgkmcnt(0)
	ds_read_b128 v[192:195], v46
	ds_read_b128 v[212:215], v46 offset:4096
	ds_read_b128 v[228:231], v46 offset:8192
	ds_read_b128 v[196:199], v47
	ds_read_b128 v[216:219], v47 offset:4096
	ds_read_b128 v[232:235], v47 offset:8192
	ds_read_b128 v[200:203], v48
	ds_read_b128 v[220:223], v48 offset:4096
	ds_read_b128 v[236:239], v48 offset:8192
	ds_read_b128 v[208:211], v49
	ds_read_b128 v[224:227], v49 offset:4096
	ds_read_b128 v[240:243], v49 offset:8192
	s_waitcnt lgkmcnt(9)
	v_mfma_f32_32x32x16_bf16 v[0:15], v[192:195], v[212:215], v[0:15]
	v_mfma_f32_32x32x16_bf16 v[16:31], v[192:195], v[228:231], v[16:31]
	s_waitcnt lgkmcnt(6)
	v_mfma_f32_32x32x16_bf16 v[0:15], v[196:199], v[216:219], v[0:15]
	v_mfma_f32_32x32x16_bf16 v[16:31], v[196:199], v[232:235], v[16:31]
	s_waitcnt lgkmcnt(3)
	v_mfma_f32_32x32x16_bf16 v[0:15], v[200:203], v[220:223], v[0:15]
	v_mfma_f32_32x32x16_bf16 v[16:31], v[200:203], v[236:239], v[16:31]
	s_waitcnt lgkmcnt(0)
	v_mfma_f32_32x32x16_bf16 v[0:15], v[208:211], v[224:227], v[0:15]
	v_mfma_f32_32x32x16_bf16 v[16:31], v[208:211], v[240:243], v[16:31]
	s_branch .Lsg5_join
.Lsg5_short:
	s_waitcnt vmcnt(12)
	ds_write_b128 v68, v[136:139]
	ds_write_b128 v68, v[140:143] offset:1024
	ds_write_b128 v68, v[144:147] offset:2048
	ds_write_b128 v68, v[148:151] offset:3072
	ds_write_b128 v68, v[152:155] offset:4096
	ds_write_b128 v68, v[156:159] offset:5120
	ds_write_b128 v68, v[160:163] offset:6144
	ds_write_b128 v68, v[164:167] offset:7168
	ds_write_b128 v68, v[168:171] offset:8192
	ds_write_b128 v68, v[172:175] offset:9216
	ds_write_b128 v68, v[180:183] offset:10240
	ds_write_b128 v68, v[184:187] offset:11264
	s_waitcnt lgkmcnt(0)
	ds_read_b128 v[192:195], v46
	ds_read_b128 v[212:215], v46 offset:4096
	ds_read_b128 v[228:231], v46 offset:8192
	ds_read_b128 v[196:199], v47
	ds_read_b128 v[216:219], v47 offset:4096
	ds_read_b128 v[232:235], v47 offset:8192
	ds_read_b128 v[200:203], v48
	ds_read_b128 v[220:223], v48 offset:4096
	ds_read_b128 v[236:239], v48 offset:8192
	ds_read_b128 v[208:211], v49
	ds_read_b128 v[224:227], v49 offset:4096
	ds_read_b128 v[240:243], v49 offset:8192
	s_waitcnt lgkmcnt(9)
	v_mfma_f32_32x32x16_bf16 v[0:15], v[192:195], v[212:215], v[0:15]
	v_mfma_f32_32x32x16_bf16 v[16:31], v[192:195], v[228:231], v[16:31]
	s_waitcnt lgkmcnt(6)
	v_mfma_f32_32x32x16_bf16 v[0:15], v[196:199], v[216:219], v[0:15]
	v_mfma_f32_32x32x16_bf16 v[16:31], v[196:199], v[232:235], v[16:31]
	s_waitcnt lgkmcnt(3)
	v_mfma_f32_32x32x16_bf16 v[0:15], v[200:203], v[220:223], v[0:15]
	v_mfma_f32_32x32x16_bf16 v[16:31], v[200:203], v[236:239], v[16:31]
	s_waitcnt lgkmcnt(0)
	v_mfma_f32_32x32x16_bf16 v[0:15], v[208:211], v[224:227], v[0:15]
	v_mfma_f32_32x32x16_bf16 v[16:31], v[208:211], v[240:243], v[16:31]
	s_waitcnt vmcnt(0)
; __device__ __forceinline__ unsigned cvt_pk_bf16(float lo, float hi) { unsigned r; asm volatile("v_cvt_pk_bf16_f32 %0, %1, %2" : "=v"(r) : "v"(lo), "v"(hi)); return r; }
; template <int CTRL> __device__ __forceinline__ float dpp_step(float t) { return t + __builtin_bit_cast(float, __builtin_amdgcn_update_dpp(0, __builtin_bit_cast(int, t), CTRL, 0xF, 0xF, true)); }
; #define LDS_BARRIER() do { asm volatile("s_waitcnt lgkmcnt(0)" ::: "memory"); __builtin_amdgcn_s_barrier(); asm volatile("" ::: "memory"); } while (0)
; template <int K, class Epi>
; __device__ __forceinline__ void small_gemm(unsigned char* lds, const bf16_t* A, const bf16_t* Bt, int row0, int br0, int br1, const Epi& E) {
;     ...
;     float* part = (float*)lds + (size_t)w * (2 * 32 * SG_P);
; #pragma unroll
;     for (int g = 0; g < 4; ++g)
; #pragma unroll
;         for (int i = 0; i < 4; ++i) { part[(8 * g + 4 * hh + i) * SG_P + r] = acc0[4 * g + i]; part[(32 + 8 * g + 4 * hh + i) * SG_P + r] = acc1[4 * g + i]; }
;     LDS_BARRIER();
;     if (tid < 256) { const int row = tid >> 3, c4 = (tid & 7) * 4; f32x4 v0 = {0.f, 0.f, 0.f, 0.f}, v1 = {0.f, 0.f, 0.f, 0.f};
; #pragma unroll
;         for (int ww = 0; ww < 8; ++ww) { const float* pp = (const float*)lds + (size_t)ww * (2 * 32 * SG_P); v0 += *(const f32x4*)(pp + row * SG_P + c4); v1 += *(const f32x4*)(pp + (32 + row) * SG_P + c4); }
;         E.small(row0 + row, br0 + c4, br1 + c4, v0, v1, spre); }
;     LDS_BARRIER();
;     __device__ __forceinline__ void small(int row, int c0, int c1, const f32x4& v0, const f32x4& v1, const SPre& sp) const {
;         float ss = 0.f;
; #pragma unroll
;         for (int gsel = 0; gsel < 2; ++gsel) { const int c = gsel ? c1 : c0; bf16_t* hb = HB + (size_t)row * DM + c; f32x4 h;
;             h = gsel ? sp.b1 : sp.b0;
;             h += (gsel ? v1 : v0);
;             u32x2 w; w.x = cvt_pk_bf16(h[0], h[1]); w.y = cvt_pk_bf16(h[2], h[3]); *(u32x2*)(HBo + (size_t)row * DM + c) = w;
;             ss += (h[0] * h[0] + h[1] * h[1]) + (h[2] * h[2] + h[3] * h[3]); }
;         ss = dpp_step<0x141>(dpp_step<0x4E>(dpp_step<0xB1>(ss)));
;         if ((threadIdx.x & 7) == 0) atomicAdd(sumsq + row, ss);
;     }
	ds_write_b128 v68, v[88:91]
	ds_write_b128 v68, v[92:95] offset:1024
	ds_write_b128 v68, v[96:99] offset:2048
	ds_write_b128 v68, v[100:103] offset:3072
	ds_write_b128 v68, v[104:107] offset:4096
	ds_write_b128 v68, v[108:111] offset:5120
	ds_write_b128 v68, v[112:115] offset:6144
	ds_write_b128 v68, v[116:119] offset:7168
	ds_write_b128 v68, v[120:123] offset:8192
	ds_write_b128 v68, v[124:127] offset:9216
	ds_write_b128 v68, v[128:131] offset:10240
	ds_write_b128 v68, v[132:135] offset:11264
	s_waitcnt lgkmcnt(0)
	ds_read_b128 v[192:195], v46
	ds_read_b128 v[212:215], v46 offset:4096
	ds_read_b128 v[228:231], v46 offset:8192
	ds_read_b128 v[196:199], v47
	ds_read_b128 v[216:219], v47 offset:4096
	ds_read_b128 v[232:235], v47 offset:8192
	ds_read_b128 v[200:203], v48
	ds_read_b128 v[220:223], v48 offset:4096
	ds_read_b128 v[236:239], v48 offset:8192
	ds_read_b128 v[208:211], v49
	ds_read_b128 v[224:227], v49 offset:4096
	ds_read_b128 v[240:243], v49 offset:8192
	s_waitcnt lgkmcnt(9)
	v_mfma_f32_32x32x16_bf16 v[0:15], v[192:195], v[212:215], v[0:15]
	v_mfma_f32_32x32x16_bf16 v[16:31], v[192:195], v[228:231], v[16:31]
	s_waitcnt lgkmcnt(6)
	v_mfma_f32_32x32x16_bf16 v[0:15], v[196:199], v[216:219], v[0:15]
	v_mfma_f32_32x32x16_bf16 v[16:31], v[196:199], v[232:235], v[16:31]
	s_waitcnt lgkmcnt(3)
	v_mfma_f32_32x32x16_bf16 v[0:15], v[200:203], v[220:223], v[0:15]
	v_mfma_f32_32x32x16_bf16 v[16:31], v[200:203], v[236:239], v[16:31]
	s_waitcnt lgkmcnt(0)
	v_mfma_f32_32x32x16_bf16 v[0:15], v[208:211], v[224:227], v[0:15]
	v_mfma_f32_32x32x16_bf16 v[16:31], v[208:211], v[240:243], v[16:31]
.Lsg5_join:
	s_barrier
	s_nop 1
	s_mulk_i32 s18, 0x2400
	v_lshlrev_b32_e32 v32, 2, v35
	v_mul_u32_u24_e32 v35, 0x90, v37
	s_add_i32 s8, s18, 0
	v_lshlrev_b32_e32 v35, 2, v35
	v_add3_u32 v37, s8, v32, v35
	v_add3_u32 v32, s8, v35, v32
	s_nop 1
	ds_write2_b32 v37, v0, v1 offset1:36
	v_add_u32_e32 v0, 0x1000, v32
	ds_write2_b32 v0, v16, v17 offset0:128 offset1:164
	ds_write2_b32 v37, v2, v3 offset0:72 offset1:108
	ds_write2_b32 v0, v18, v19 offset0:200 offset1:236
	v_add_u32_e32 v0, 0x400, v37
	v_add_u32_e32 v1, 0x1400, v32
	ds_write2_b32 v0, v4, v5 offset0:32 offset1:68
	ds_write2_b32 v1, v20, v21 offset0:160 offset1:196
	ds_write2_b32 v0, v6, v7 offset0:104 offset1:140
	v_add_u32_e32 v0, 0x1600, v32
	ds_write2_b32 v0, v22, v23 offset0:104 offset1:140
	v_add_u32_e32 v0, 0x800, v37
	v_add_u32_e32 v1, 0x1800, v32
	ds_write2_b32 v0, v8, v9 offset0:64 offset1:100
	ds_write2_b32 v1, v24, v25 offset0:192 offset1:228
	ds_write2_b32 v0, v10, v11 offset0:136 offset1:172
	v_add_u32_e32 v0, 0x1c00, v32
	ds_write2_b32 v0, v26, v27 offset0:8 offset1:44
	v_add_u32_e32 v0, 0xc00, v37
	v_add_u32_e32 v1, 0x1e00, v32
	ds_write2_b32 v0, v12, v13 offset0:96 offset1:132
	ds_write2_b32 v1, v28, v29 offset0:96 offset1:132
	ds_write2_b32 v0, v14, v15 offset0:168 offset1:204
	v_add_u32_e32 v0, 0x2000, v32
	ds_write2_b32 v0, v30, v31 offset0:40 offset1:76
	s_waitcnt lgkmcnt(0)
	s_barrier
	s_and_saveexec_b64 s[8:9], s[6:7]
	s_cbranch_execz .LBB0_788
	v_ashrrev_i32_e32 v30, 3, v52
	v_mul_lo_u32 v0, v30, s13
	v_lshlrev_b32_e32 v1, 2, v53
	v_add3_u32 v31, 0, v0, v1
	ds_read_b128 v[0:3], v31
	ds_read_b128 v[4:7], v31 offset:4608
	ds_read_b128 v[8:11], v31 offset:9216
	ds_read_b128 v[12:15], v31 offset:64512
	v_mov_b32_e32 v37, v33
	s_waitcnt lgkmcnt(3)
	v_pk_add_f32 v[16:17], v[2:3], 0 op_sel_hi:[1,0]
	v_pk_add_f32 v[18:19], v[0:1], 0 op_sel_hi:[1,0]
	ds_read_b128 v[0:3], v31 offset:13824
	s_waitcnt lgkmcnt(3)
	v_pk_add_f32 v[20:21], v[6:7], 0 op_sel_hi:[1,0]
	v_pk_add_f32 v[22:23], v[4:5], 0 op_sel_hi:[1,0]
	ds_read_b128 v[4:7], v31 offset:18432
	s_waitcnt lgkmcnt(3)
	v_pk_add_f32 v[16:17], v[16:17], v[10:11]
	v_pk_add_f32 v[18:19], v[18:19], v[8:9]
	s_waitcnt lgkmcnt(1)
	v_pk_add_f32 v[20:21], v[20:21], v[2:3]
	ds_read_b128 v[8:11], v31 offset:23040
	v_pk_add_f32 v[22:23], v[22:23], v[0:1]
	ds_read_b128 v[0:3], v31 offset:27648
	s_waitcnt lgkmcnt(2)
	v_pk_add_f32 v[6:7], v[16:17], v[6:7]
	v_pk_add_f32 v[16:17], v[18:19], v[4:5]
	s_waitcnt lgkmcnt(1)
	v_pk_add_f32 v[10:11], v[20:21], v[10:11]
	v_pk_add_f32 v[24:25], v[22:23], v[8:9]
	s_waitcnt lgkmcnt(0)
	v_pk_add_f32 v[26:27], v[6:7], v[2:3]
	ds_read_b128 v[2:5], v31 offset:32256
	v_pk_add_f32 v[28:29], v[16:17], v[0:1]
	ds_read_b128 v[6:9], v31 offset:36864
	v_add_u32_e32 v0, 0xfc00, v31
	ds_read_b128 v[20:23], v31 offset:41472
	ds_read_b128 v[16:19], v0 offset:4608
	s_waitcnt lgkmcnt(3)
	v_pk_add_f32 v[4:5], v[10:11], v[4:5]
	v_pk_add_f32 v[10:11], v[24:25], v[2:3]
	ds_read_b128 v[0:3], v31 offset:46080
	s_waitcnt lgkmcnt(3)
	v_pk_add_f32 v[8:9], v[26:27], v[8:9]
	v_pk_add_f32 v[24:25], v[28:29], v[6:7]
	s_waitcnt lgkmcnt(2)
	v_pk_add_f32 v[22:23], v[4:5], v[22:23]
	ds_read_b128 v[4:7], v31 offset:50688
	v_pk_add_f32 v[20:21], v[10:11], v[20:21]
	s_waitcnt lgkmcnt(1)
	v_pk_add_f32 v[26:27], v[8:9], v[2:3]
	ds_read_b128 v[8:11], v31 offset:55296
	v_pk_add_f32 v[24:25], v[24:25], v[0:1]
	ds_read_b128 v[0:3], v31 offset:59904
	s_waitcnt lgkmcnt(2)
	v_pk_add_f32 v[4:5], v[20:21], v[4:5]
	v_pk_add_f32 v[6:7], v[22:23], v[6:7]
	s_waitcnt lgkmcnt(1)
	v_pk_add_f32 v[8:9], v[24:25], v[8:9]
	v_pk_add_f32 v[10:11], v[26:27], v[10:11]
	s_waitcnt lgkmcnt(0)
	v_pk_add_f32 v[0:1], v[4:5], v[0:1]
	v_pk_add_f32 v[2:3], v[6:7], v[2:3]
	v_pk_add_f32 v[6:7], v[8:9], v[12:13]
	v_pk_add_f32 v[8:9], v[0:1], v[16:17]
	v_add_u32_e32 v0, s17, v30
	v_pk_add_f32 v[4:5], v[10:11], v[14:15]
	v_ashrrev_i32_e32 v1, 31, v0
	v_lshlrev_b64 v[10:11], 11, v[0:1]
	v_pk_add_f32 v[4:5], v[44:45], v[4:5]
	v_pk_add_f32 v[6:7], v[42:43], v[6:7]
	v_lshl_add_u64 v[10:11], s[84:85], 0, v[10:11]
	v_cvt_pk_bf16_f32 v12, v6, v7
	v_cvt_pk_bf16_f32 v13, v4, v5
	v_mul_f32_e32 v7, v7, v7
	v_mul_f32_e32 v5, v5, v5
	v_pk_add_f32 v[2:3], v[2:3], v[18:19]
	v_lshl_add_u64 v[14:15], v[10:11], 0, v[36:37]
	v_fmac_f32_e32 v7, v6, v6
	v_fmac_f32_e32 v5, v4, v4
	global_store_dwordx2 v[14:15], v[12:13], off
	v_add_f32_e32 v12, v7, v5
	v_pk_add_f32 v[2:3], v[40:41], v[2:3]
	v_pk_add_f32 v[4:5], v[38:39], v[8:9]
	v_mov_b32_e32 v35, v33
	v_cvt_pk_bf16_f32 v6, v4, v5
	v_cvt_pk_bf16_f32 v7, v2, v3
	v_mul_f32_e32 v5, v5, v5
	v_mul_f32_e32 v3, v3, v3
	v_fmac_f32_e32 v5, v4, v4
	v_fmac_f32_e32 v3, v2, v2
	v_add_f32_e32 v2, v5, v3
	v_add_f32_e32 v2, v12, v2
	v_lshl_add_u64 v[8:9], v[10:11], 0, v[34:35]
	global_store_dwordx2 v[8:9], v[6:7], off offset:64
	v_add_f32_dpp v2, v2, v2 quad_perm:[1,0,3,2] row_mask:0xf bank_mask:0xf bound_ctrl:1
	s_nop 1
	v_add_f32_dpp v2, v2, v2 quad_perm:[2,3,0,1] row_mask:0xf bank_mask:0xf bound_ctrl:1
	s_nop 1
	v_mov_b32_dpp v3, v2 row_half_mirror row_mask:0xf bank_mask:0xf bound_ctrl:1
	s_and_b64 exec, exec, vcc
	s_cbranch_execz .LBB0_788
	v_lshl_add_u64 v[0:1], v[0:1], 2, s[14:15]
	v_add_f32_e32 v2, v2, v3
	global_atomic_add_f32 v[0:1], v2, off
	s_branch .LBB0_788
